# attention slow-path bias lookup: padded 512-entry LUT, batched ds_read2 with immediate offsets
# speedup vs baseline: 1.0051x; 1.0051x over previous
; __device__ __forceinline__ void attn_unit(LAS unsigned char* lds, const bf16_t* __restrict__ U3, const bf16_t* __restrict__ VT, bf16_t* __restrict__ MIX, ...
;     ...
;     if (tid < 257) { const int rel = tid - 128, n = rel < 0 ? -rel : rel;
;         int bk = n < 8 ? n : 8 + (n >= 12) + (n >= 16) + (n >= 23) + (n >= 32) + (n >= 46) + (n >= 64) + (n >= 91);
;         if (rel > 0) bk += 16;
;         lut[tid] = tbl[bk * 4 + h] * LOG2E; }
.LBB0_509:
	v_mov_b32_e32 v155, v202
	s_movk_i32 s12, 0x200
	s_nop 0
	v_readfirstlane_b32 s73, v155
	v_cmp_gt_i32_e32 vcc, s12, v155
	s_and_saveexec_b64 s[12:13], vcc
	s_cbranch_execz .LBB0_513
	v_add_u32_e32 v0, 0xfffffee0, v155
	v_sub_u32_e32 v1, 0x120, v155
	v_cmp_gt_i32_e32 vcc, 0x120, v155
	s_nop 1
	v_cndmask_b32_e32 v0, v0, v1, vcc
	v_cmp_lt_i32_e32 vcc, 7, v0
	s_and_saveexec_b64 s[14:15], vcc
	s_cbranch_execz .LBB0_512
	v_cmp_lt_u32_e32 vcc, 11, v0
	s_movk_i32 s24, 0x5a
	s_nop 0
	v_cndmask_b32_e64 v1, 8, 9, vcc
	v_cmp_lt_u32_e32 vcc, 15, v0
	s_nop 1
	v_cndmask_b32_e64 v2, 0, 1, vcc
	v_cmp_lt_u32_e32 vcc, 22, v0
	s_nop 1
	v_addc_co_u32_e32 v1, vcc, v1, v2, vcc
	v_cmp_lt_u32_e32 vcc, 31, v0
	s_nop 1
	v_cndmask_b32_e64 v2, 0, 1, vcc
	v_cmp_lt_u32_e32 vcc, 45, v0
	s_nop 1
	v_addc_co_u32_e32 v1, vcc, v1, v2, vcc
	v_cmp_lt_u32_e32 vcc, 63, v0
	s_nop 1
	v_cndmask_b32_e64 v2, 0, 1, vcc
	v_cmp_lt_u32_e32 vcc, s24, v0
	s_nop 1
	v_addc_co_u32_e32 v0, vcc, v1, v2, vcc
.LBB0_512:
	s_or_b64 exec, exec, s[14:15]
	v_lshlrev_b32_e32 v0, 2, v0
	s_load_dwordx2 s[14:15], s[0:1], 0x18
	v_add_u32_e32 v1, 64, v0
	v_cmp_lt_i32_e32 vcc, 0x120, v155
	s_nop 1
	v_cndmask_b32_e32 v0, v0, v1, vcc
	v_or_b32_e32 v0, s36, v0
	v_ashrrev_i32_e32 v1, 31, v0
	s_waitcnt lgkmcnt(0)
	v_lshl_add_u64 v[0:1], v[0:1], 2, s[14:15]
	global_load_dword v0, v[0:1], off
	v_lshl_add_u32 v1, v155, 2, 0
	v_add_u32_e32 v1, 0x20000, v1
	s_waitcnt vmcnt(0)
	v_mul_f32_e32 v0, 0x3fb8aa3b, v0
	ds_write_b32 v1, v0
; __device__ __forceinline__ void attn_unit(LAS unsigned char* lds, const bf16_t* __restrict__ U3, const bf16_t* __restrict__ VT, bf16_t* __restrict__ MIX, ...
;     ...
;     bf16x8 qr[4];
;     { const bf16_t* qp = U3 + (size_t)(rowbase + q - NMETA) * 1536 + h * 128 + c * 64 + hi * 8;
; #pragma unroll
;       for (int d0 = 0; d0 < 4; ++d0) qr[d0] = *(const bf16x8*)(qp + d0 * 16); }
;     const bf16_t* kg[2]; const bf16_t* vg[2];
; #pragma unroll
;     for (int i = 0; i < 2; ++i) { const int row = 4 * (i * 8 + w) + (lane >> 4), kch = (lane & 15) ^ (row & 15);
;         kg[i] = U3 + (size_t)row * 1536 + 512 + h * 128 + kch * 8;
;         const int rp = row, p = (lane & 15) ^ (rp & 15), dv = 2 * rp + (p >> 3), ch = p & 7;
;         vg[i] = VT + (size_t)(h * 128 + dv) * MPAD + ch * 8; }
;     ...
;     const int pi = (r32 & 0x13) | ((r32 & 4) << 1) | ((r32 & 8) >> 1);
;     unsigned koff[4], voff[4];
; #pragma unroll
;     for (int d0 = 0; d0 < 4; ++d0) koff[d0] = pi * 256 + (((c * 8 + d0 * 2 + hi) ^ (pi & 15)) << 4);
; #pragma unroll
;     for (int j = 0; j < 4; ++j) voff[j] = 16384 + (r32 >> 1) * 256 + (((((r32 & 1) << 3) + 2 * j + hi) ^ (r32 >> 1)) << 4);
;     ATT_DMA(0, 0); ATT_DMA(1, 1);
;     asm volatile("s_waitcnt vmcnt(4)" ::: "memory");
;     asm volatile("s_waitcnt lgkmcnt(0)" ::: "memory"); __builtin_amdgcn_s_barrier(); asm volatile("" ::: "memory");
;     const float bL = lut[0], bR = lut[256];
;     f32x16 o[4];
; #pragma unroll
;     for (int d0 = 0; d0 < 4; ++d0)
; #pragma unroll
;         for (int r = 0; r < 16; ++r) o[d0][r] = 0.f;
;     float mhat = 0.f, l = 0.f;
;     bf16x8 pf[4];
; #pragma unroll
;     for (int j = 0; j < 4; ++j) pf[j] = (bf16x8){0, 0, 0, 0, 0, 0, 0, 0};
;     int slot = 0, slotp = 0, slot2 = 2;
.LBB0_513:
	s_or_b64 exec, exec, s[12:13]
	s_lshl_b32 s12, s17, 13
	s_ashr_i32 s14, s73, 6
	s_ashr_i32 s74, s73, 8
	s_add_i32 s12, s12, 0x8000
	s_lshl_b32 s13, s17, 11
	s_and_b64 s[10:11], exec, s[10:11]
	s_cselect_b32 s10, s13, s12
	s_and_b32 s72, s14, 3
	s_lshl_b32 s11, s16, 7
	s_lshl_b32 s12, s72, 5
	s_or_b32 s76, s12, s11
	v_and_b32_e32 v158, 31, v155
	s_or_b32 s62, s76, 16
	v_add_u32_e32 v168, s62, v158
	s_add_i32 s63, s10, -16
	v_add_u32_e32 v2, s63, v168
	v_mov_b64_e32 v[0:1], s[20:21]
	v_mad_i64_i32 v[2:3], s[12:13], v2, s69, v[0:1]
	s_lshl_b32 s12, s74, 6
	v_bfe_u32 v159, v155, 5, 1
	s_ashr_i32 s13, s12, 31
	s_lshl_b32 s11, s14, 2
	v_bfe_u32 v156, v155, 4, 2
	v_lshl_add_u64 v[2:3], s[12:13], 1, v[2:3]
	v_lshlrev_b32_e32 v160, 4, v159
	v_or_b32_e32 v8, s11, v156
	v_lshl_add_u64 v[2:3], v[2:3], 0, v[160:161]
	v_bitop3_b32 v4, v8, 15, v155 bitop3:0x48
	global_load_dwordx4 v[112:115], v[2:3], off
	global_load_dwordx4 v[116:119], v[2:3], off offset:32
	global_load_dwordx4 v[120:123], v[2:3], off offset:64
	global_load_dwordx4 v[124:127], v[2:3], off offset:96
	v_bitop3_b32 v6, s11, v155, v156 bitop3:0x36
	v_mad_i64_i32 v[2:3], s[12:13], v8, s69, v[0:1]
	v_lshlrev_b32_e32 v4, 4, v4
	v_mov_b32_e32 v5, v161
	v_lshl_add_u64 v[146:147], v[2:3], 0, v[4:5]
	v_bfe_u32 v2, v6, 3, 1
	v_lshl_add_u32 v3, v8, 1, s37
	v_or_b32_e32 v4, v2, v3
	v_mov_b64_e32 v[2:3], s[52:53]
	v_lshlrev_b32_e32 v6, 4, v6
	v_mad_i64_i32 v[4:5], s[12:13], v4, s41, v[2:3]
	v_and_b32_e32 v6, 0x70, v6
	v_mov_b32_e32 v7, v161
	v_lshl_add_u64 v[148:149], v[4:5], 0, v[6:7]
	v_add_u32_e32 v6, 32, v8
	v_bitop3_b32 v4, v6, 15, v155 bitop3:0x48
	v_xor_b32_e32 v7, v6, v155
	v_mad_i64_i32 v[0:1], s[12:13], v6, s69, v[0:1]
	v_lshlrev_b32_e32 v4, 4, v4
	v_mov_b32_e32 v5, v161
	v_lshl_add_u64 v[150:151], v[0:1], 0, v[4:5]
	v_bfe_u32 v0, v7, 3, 1
	v_lshl_add_u32 v1, v6, 1, s37
	v_or_b32_e32 v0, v0, v1
	v_mad_i64_i32 v[0:1], s[12:13], v0, s41, v[2:3]
	v_lshlrev_b32_e32 v2, 4, v7
	v_and_b32_e32 v2, 0x70, v2
	v_mov_b32_e32 v3, v161
	s_lshl_b32 s11, s14, 10
	v_lshl_add_u64 v[152:153], v[0:1], 0, v[2:3]
	s_add_i32 s77, s11, 0
	v_mad_i64_i32 v[0:1], s[12:13], s10, v212, v[146:147]
	v_lshl_add_u64 v[0:1], v[0:1], 0, s[86:87]
	s_mov_b32 m0, s77
	s_ashr_i32 s11, s10, 31
	global_load_lds_dwordx4 v[0:1], off
	v_mad_i64_i32 v[0:1], s[12:13], s10, v212, v[150:151]
	v_lshl_add_u64 v[0:1], v[0:1], 0, s[86:87]
	s_add_i32 m0, s77, 0x2000
	s_lshl_b64 s[12:13], s[10:11], 1
	global_load_lds_dwordx4 v[0:1], off
	v_lshl_add_u64 v[0:1], v[148:149], 0, s[12:13]
	s_add_i32 m0, s77, 0x4000
	s_or_b32 s11, s10, 64
	global_load_lds_dwordx4 v[0:1], off
	v_lshl_add_u64 v[2:3], v[152:153], 0, s[12:13]
	s_add_i32 m0, s77, 0x6000
	v_mad_i64_i32 v[4:5], s[12:13], s11, v212, v[146:147]
	global_load_lds_dwordx4 v[2:3], off
	s_add_i32 m0, s77, 0x8000
	v_lshl_add_u64 v[4:5], v[4:5], 0, s[86:87]
	global_load_lds_dwordx4 v[4:5], off
	v_mad_i64_i32 v[4:5], s[12:13], s11, v212, v[150:151]
	v_lshl_add_u64 v[4:5], v[4:5], 0, s[86:87]
	s_add_i32 m0, s77, 0xa000
	v_lshl_add_u64 v[0:1], v[0:1], 0, s[90:91]
	global_load_lds_dwordx4 v[4:5], off
	s_add_i32 m0, s77, 0xc000
	s_add_i32 s79, 0, 0x20000
	global_load_lds_dwordx4 v[0:1], off
	v_lshl_add_u64 v[0:1], v[2:3], 0, s[90:91]
	s_add_i32 m0, s77, 0xe000
	v_lshl_or_b32 v3, s74, 3, v159
	global_load_lds_dwordx4 v[0:1], off
	v_and_b32_e32 v0, 19, v155
	v_lshlrev_b32_e32 v1, 1, v155
	v_and_or_b32 v0, v1, 8, v0
	v_lshrrev_b32_e32 v1, 1, v155
	v_and_b32_e32 v1, 4, v1
	v_or_b32_e32 v2, v0, v1
	v_bitop3_b32 v0, v0, 15, v1 bitop3:0xc8
	v_bitop3_b32 v1, v2, v3, 15 bitop3:0x6c
	v_lshlrev_b32_e32 v171, 8, v2
	v_lshlrev_b32_e32 v173, 4, v1
	v_bitop3_b32 v1, v3, v0, 2 bitop3:0x36
	v_lshlrev_b32_e32 v2, 3, v155
	v_lshlrev_b32_e32 v174, 4, v1
	v_bitop3_b32 v1, v3, v0, 4 bitop3:0x36
	v_bitop3_b32 v0, v3, v0, 6 bitop3:0x36
	v_and_b32_e32 v2, 8, v2
	v_lshlrev_b32_e32 v176, 4, v0
	v_bfe_u32 v0, v155, 1, 4
	v_or_b32_e32 v3, v2, v159
	s_waitcnt vmcnt(4)
	v_lshlrev_b32_e32 v175, 4, v1
	v_lshlrev_b32_e32 v1, 8, v0
	v_bitop3_b32 v2, v2, v0, v159 bitop3:0x36
	v_bitop3_b32 v4, v3, v0, 2 bitop3:0x36
	v_bitop3_b32 v5, v3, v0, 4 bitop3:0x36
	v_bitop3_b32 v0, v3, v0, 6 bitop3:0x36
	s_waitcnt lgkmcnt(0)
	s_barrier
	v_mov_b32_e32 v3, s79
	v_mov_b32_e32 v6, s50
	ds_read_b32 v178, v3 offset:640
	ds_read_b32 v180, v6 offset:640
	v_mov_b32_e32 v48, v161
	v_mov_b32_e32 v49, v161
	v_mov_b32_e32 v140, v161
	v_mov_b32_e32 v141, v161
	v_lshl_or_b32 v179, v2, 4, v1
	v_lshl_or_b32 v177, v4, 4, v1
	v_lshl_or_b32 v172, v5, 4, v1
	v_lshl_or_b32 v170, v0, 4, v1
	s_lshl_b32 s85, s75, 6
	v_mov_b32_e32 v50, v161
	v_mov_b32_e32 v51, v161
	v_mov_b32_e32 v52, v161
	v_mov_b32_e32 v53, v161
	v_mov_b32_e32 v54, v161
	v_mov_b32_e32 v55, v161
	v_mov_b32_e32 v56, v161
	v_mov_b32_e32 v57, v161
	v_mov_b32_e32 v58, v161
	v_mov_b32_e32 v59, v161
	v_mov_b32_e32 v60, v161
	v_mov_b32_e32 v61, v161
	v_mov_b32_e32 v62, v161
	v_mov_b32_e32 v63, v161
	v_mov_b32_e32 v142, v161
	v_mov_b32_e32 v143, v161
	v_mov_b64_e32 v[136:137], v[140:141]
	v_mov_b64_e32 v[132:133], v[140:141]
	v_mov_b64_e32 v[128:129], v[140:141]
	v_mov_b64_e32 v[32:33], v[48:49]
	v_mov_b64_e32 v[16:17], v[48:49]
	v_mov_b64_e32 v[0:1], v[48:49]
	v_lshlrev_b32_e32 v157, 3, v159
	s_mov_b32 s78, 2
	s_or_b32 s84, s10, 0x80
	s_add_i32 s97, s85, 64
	s_mov_b32 s33, 0
	v_mov_b32_e32 v169, 0
	v_mov_b64_e32 v[138:139], v[142:143]
	v_mov_b64_e32 v[134:135], v[142:143]
	v_mov_b64_e32 v[130:131], v[142:143]
	v_mov_b64_e32 v[34:35], v[50:51]
	v_mov_b64_e32 v[36:37], v[52:53]
	v_mov_b64_e32 v[38:39], v[54:55]
	v_mov_b64_e32 v[40:41], v[56:57]
	v_mov_b64_e32 v[42:43], v[58:59]
	v_mov_b64_e32 v[44:45], v[60:61]
	v_mov_b64_e32 v[46:47], v[62:63]
	v_mov_b64_e32 v[18:19], v[50:51]
	v_mov_b64_e32 v[20:21], v[52:53]
	v_mov_b64_e32 v[22:23], v[54:55]
	v_mov_b64_e32 v[24:25], v[56:57]
	v_mov_b64_e32 v[26:27], v[58:59]
	v_mov_b64_e32 v[28:29], v[60:61]
	v_mov_b64_e32 v[30:31], v[62:63]
	v_mov_b64_e32 v[2:3], v[50:51]
	v_mov_b64_e32 v[4:5], v[52:53]
	v_mov_b64_e32 v[6:7], v[54:55]
	v_mov_b64_e32 v[8:9], v[56:57]
	v_mov_b64_e32 v[10:11], v[58:59]
	v_mov_b64_e32 v[12:13], v[60:61]
	v_mov_b64_e32 v[14:15], v[62:63]
	v_mov_b32_e32 v181, 0
	s_mov_b32 s10, 0
	s_mov_b32 s16, 0
	s_mov_b32 s45, 2
	s_waitcnt vmcnt(0)

; #define LAS __attribute__((address_space(3)))
; __device__ __forceinline__ void attn_unit(LAS unsigned char* lds, const bf16_t* __restrict__ U3, const bf16_t* __restrict__ VT, bf16_t* __restrict__ MIX, ...
;     ...
; #pragma unroll 1
;     for (int t = 0; t < NT; ++t) {
;         const bool mt = (t == NT - 1); const int k0 = mt ? 0 : NMETA + t * 64; LAS unsigned char* buf = lds + slot * STAGE; LAS unsigned char* pbuf = lds + slotp * STAGE;
;         const bool ahead = t + 2 < NT;
;         if (ahead) ATT_DMA(t + 2, slot2);
;         const int relmax = k0 + 63 - qw0, relmin = k0 - (qw0 + 31);
;         const bool farl = relmax <= -91, farr = relmin >= 91;
;         const bool slow = !(farl || farr) || mt;
;         f32x16 p0, p1;
;         ATT_SCORES();
.LBB0_516:
	s_add_i32 s14, s33, 16
	s_cmp_eq_u32 s85, s33
	s_cselect_b64 s[10:11], -1, 0
	s_and_b64 s[12:13], s[10:11], exec
	s_cselect_b32 s56, 0, s14
	s_lshl_b32 s12, s81, 15
	s_add_i32 s43, s12, 0
	s_sub_i32 s12, s56, s62
	s_sub_i32 s13, s56, s76
	s_add_i32 s12, s12, 63
	s_sub_i32 s13, s13, 47
	s_cmpk_gt_i32 s12, 0xffa5
	s_cselect_b64 vcc, -1, 0
	s_cmpk_lt_i32 s13, 0x5b
	s_cselect_b64 s[12:13], -1, 0
	s_and_b64 s[12:13], vcc, s[12:13]
	s_waitcnt lgkmcnt(0)
	v_cndmask_b32_e32 v64, v178, v180, vcc
	s_or_b64 s[12:13], s[10:11], s[12:13]
	v_cndmask_b32_e64 v64, v64, 0, s[12:13]
	v_sub_f32_e32 v80, v64, v181
	v_add_u32_e32 v64, s43, v173
	v_add_u32_e32 v182, v64, v171
	v_add_u32_e32 v64, s43, v174
	v_add_u32_e32 v183, v64, v171
	v_add_u32_e32 v64, s43, v175
	v_add_u32_e32 v184, v64, v171
	v_add_u32_e32 v64, s43, v176
	v_add_u32_e32 v185, v64, v171
	ds_read_b128 v[96:99], v182
	ds_read_b128 v[186:189], v182 offset:8192
	ds_read_b128 v[190:193], v183
	ds_read_b128 v[194:197], v183 offset:8192
	ds_read_b128 v[198:201], v184
	ds_read_b128 v[218:221], v184 offset:8192
	ds_read_b128 v[222:225], v185
	ds_read_b128 v[226:229], v185 offset:8192
	v_mov_b32_e32 v81, v80
	v_mov_b32_e32 v82, v80
	v_mov_b32_e32 v83, v80
	v_mov_b32_e32 v84, v80
	v_mov_b32_e32 v85, v80
	v_mov_b32_e32 v86, v80
	v_mov_b32_e32 v87, v80
	v_mov_b32_e32 v88, v80
	v_mov_b32_e32 v89, v80
	v_mov_b32_e32 v90, v80
	v_mov_b32_e32 v91, v80
	v_mov_b32_e32 v92, v80
	v_mov_b32_e32 v93, v80
	v_mov_b32_e32 v94, v80
	v_mov_b32_e32 v95, v80
	s_setprio 1
	s_waitcnt lgkmcnt(0)
	v_mfma_f32_32x32x16_bf16 v[64:79], v[96:99], v[112:115], v[80:95]
	v_mfma_f32_32x32x16_bf16 v[96:111], v[186:189], v[112:115], v[80:95]
	v_mfma_f32_32x32x16_bf16 v[64:79], v[190:193], v[116:119], v[64:79]
	v_mfma_f32_32x32x16_bf16 v[96:111], v[194:197], v[116:119], v[96:111]
	v_mfma_f32_32x32x16_bf16 v[64:79], v[198:201], v[120:123], v[64:79]
	v_mfma_f32_32x32x16_bf16 v[96:111], v[218:221], v[120:123], v[96:111]
	v_mfma_f32_32x32x16_bf16 v[64:79], v[222:225], v[124:127], v[64:79]
	v_mfma_f32_32x32x16_bf16 v[96:111], v[226:229], v[124:127], v[96:111]
	s_setprio 0
	v_cndmask_b32_e64 v186, 0, 1, s[12:13]
	v_cmp_ne_u32_e64 s[14:15], 1, v186
	s_andn2_b64 vcc, exec, s[12:13]
	s_cbranch_vccnz .LBB0_518
	v_or_b32_e32 v186, s56, v157
	v_sub_u32_e32 v186, v186, v168
	v_max_i32_e32 v186, 0xfffffee0, v186
	v_min_i32_e32 v186, 0xa8, v186
	s_add_i32 s98, s79, 0x480
	v_lshl_add_u32 v186, v186, 2, s98
	s_and_b64 vcc, exec, s[10:11]
	s_cbranch_vccnz .Latt_slow_mt_a
	ds_read2_b32 v[234:235], v186 offset1:1
	ds_read2_b32 v[236:237], v186 offset0:2 offset1:3
	ds_read2_b32 v[238:239], v186 offset0:4 offset1:5
	ds_read2_b32 v[240:241], v186 offset0:6 offset1:7
	ds_read2_b32 v[242:243], v186 offset0:16 offset1:17
	ds_read2_b32 v[244:245], v186 offset0:18 offset1:19
	ds_read2_b32 v[246:247], v186 offset0:20 offset1:21
	ds_read2_b32 v[248:249], v186 offset0:22 offset1:23
	ds_read2_b32 v[250:251], v186 offset0:32 offset1:33
	ds_read2_b32 v[252:253], v186 offset0:34 offset1:35
	ds_read2_b32 v[188:189], v186 offset0:36 offset1:37
	ds_read2_b32 v[190:191], v186 offset0:38 offset1:39
	ds_read2_b32 v[192:193], v186 offset0:48 offset1:49
	ds_read2_b32 v[194:195], v186 offset0:50 offset1:51
	ds_read2_b32 v[196:197], v186 offset0:52 offset1:53
	ds_read2_b32 v[198:199], v186 offset0:54 offset1:55
	s_waitcnt lgkmcnt(0)
	v_add_f32_e32 v64, v64, v234
	v_add_f32_e32 v65, v65, v235
	v_add_f32_e32 v66, v66, v236
	v_add_f32_e32 v67, v67, v237
	v_add_f32_e32 v68, v68, v238
	v_add_f32_e32 v69, v69, v239
	v_add_f32_e32 v70, v70, v240
	v_add_f32_e32 v71, v71, v241
	v_add_f32_e32 v72, v72, v242
	v_add_f32_e32 v73, v73, v243
	v_add_f32_e32 v74, v74, v244
	v_add_f32_e32 v75, v75, v245
	v_add_f32_e32 v76, v76, v246
	v_add_f32_e32 v77, v77, v247
	v_add_f32_e32 v78, v78, v248
	v_add_f32_e32 v79, v79, v249
	v_add_f32_e32 v96, v96, v250
	v_add_f32_e32 v97, v97, v251
	v_add_f32_e32 v98, v98, v252
	v_add_f32_e32 v99, v99, v253
	v_add_f32_e32 v100, v100, v188
	v_add_f32_e32 v101, v101, v189
	v_add_f32_e32 v102, v102, v190
	v_add_f32_e32 v103, v103, v191
	v_add_f32_e32 v104, v104, v192
	v_add_f32_e32 v105, v105, v193
	v_add_f32_e32 v106, v106, v194
	v_add_f32_e32 v107, v107, v195
	v_add_f32_e32 v108, v108, v196
	v_add_f32_e32 v109, v109, v197
	v_add_f32_e32 v110, v110, v198
	v_add_f32_e32 v111, v111, v199
	s_branch .LBB0_518
.Latt_slow_mt_a:
	ds_read2_b32 v[234:235], v186 offset1:1
	ds_read2_b32 v[236:237], v186 offset0:2 offset1:3
	ds_read2_b32 v[238:239], v186 offset0:4 offset1:5
	ds_read2_b32 v[240:241], v186 offset0:6 offset1:7
	s_waitcnt lgkmcnt(0)
	v_add_f32_e32 v64, v64, v234
	v_add_f32_e32 v65, v65, v235
	v_add_f32_e32 v66, v66, v236
	v_add_f32_e32 v67, v67, v237
	v_add_f32_e32 v68, v68, v238
	v_add_f32_e32 v69, v69, v239
	v_add_f32_e32 v70, v70, v240
	v_add_f32_e32 v71, v71, v241
	v_mov_b32_e32 v72, v215
	v_mov_b32_e32 v73, v215
	v_mov_b32_e32 v74, v215
	v_mov_b32_e32 v75, v215
	v_mov_b32_e32 v76, v215
	v_mov_b32_e32 v77, v215
	v_mov_b32_e32 v78, v215
	v_mov_b32_e32 v79, v215
	v_mov_b32_e32 v96, v215
	v_mov_b32_e32 v97, v215
	v_mov_b32_e32 v98, v215
	v_mov_b32_e32 v99, v215
	v_mov_b32_e32 v100, v215
	v_mov_b32_e32 v101, v215
	v_mov_b32_e32 v102, v215
	v_mov_b32_e32 v103, v215
	v_mov_b32_e32 v104, v215
	v_mov_b32_e32 v105, v215
	v_mov_b32_e32 v106, v215
	v_mov_b32_e32 v107, v215
	v_mov_b32_e32 v108, v215
	v_mov_b32_e32 v109, v215
	v_mov_b32_e32 v110, v215
	v_mov_b32_e32 v111, v215

; __device__ __forceinline__ void attn_unit(LAS unsigned char* lds, const bf16_t* __restrict__ U3, const bf16_t* __restrict__ VT, bf16_t* __restrict__ MIX, ...
;     ...
;         if (t == 0 || __any(!(ssum <= 8192.0f))) {
;             if (t != 0) ATT_SCORES();
.LBB0_520:
	v_cndmask_b32_e64 v187, 0, 1, s[26:27]
	v_cmp_ne_u32_e64 s[16:17], 1, v187
	s_andn2_b64 vcc, exec, s[26:27]
	s_mov_b64 s[26:27], -1
	s_cbranch_vccnz .LBB0_525
	s_mov_b32 s26, 0x46000000
	v_cmp_nge_f32_e32 vcc, s26, v186
	s_cbranch_vccz .LBB0_533
	ds_read_b128 v[96:99], v182
	ds_read_b128 v[100:103], v182 offset:8192
	ds_read_b128 v[104:107], v183
	ds_read_b128 v[108:111], v183 offset:8192
	ds_read_b128 v[188:191], v184
	ds_read_b128 v[192:195], v184 offset:8192
	ds_read_b128 v[196:199], v185
	ds_read_b128 v[182:185], v185 offset:8192
	s_setprio 1
	s_waitcnt lgkmcnt(0)
	v_mfma_f32_32x32x16_bf16 v[64:79], v[96:99], v[112:115], v[80:95]
	v_mfma_f32_32x32x16_bf16 v[80:95], v[100:103], v[112:115], v[80:95]
	v_mfma_f32_32x32x16_bf16 v[64:79], v[104:107], v[116:119], v[64:79]
	v_mfma_f32_32x32x16_bf16 v[80:95], v[108:111], v[116:119], v[80:95]
	v_mfma_f32_32x32x16_bf16 v[64:79], v[188:191], v[120:123], v[64:79]
	v_mfma_f32_32x32x16_bf16 v[80:95], v[192:195], v[120:123], v[80:95]
	v_mfma_f32_32x32x16_bf16 v[64:79], v[196:199], v[124:127], v[64:79]
	v_mfma_f32_32x32x16_bf16 v[80:95], v[182:185], v[124:127], v[80:95]
	s_setprio 0
	s_and_b64 vcc, exec, s[14:15]
	s_cbranch_vccnz .LBB0_524
	v_or_b32_e32 v96, s56, v157
	v_sub_u32_e32 v96, v96, v168
	v_max_i32_e32 v96, 0xfffffee0, v96
	v_min_i32_e32 v96, 0xa8, v96
	s_add_i32 s98, s79, 0x480
	v_lshl_add_u32 v96, v96, 2, s98
	s_and_b64 vcc, exec, s[10:11]
	s_cbranch_vccnz .Latt_slow_mt_b
	ds_read2_b32 v[234:235], v96 offset1:1
	ds_read2_b32 v[236:237], v96 offset0:2 offset1:3
	ds_read2_b32 v[238:239], v96 offset0:4 offset1:5
	ds_read2_b32 v[240:241], v96 offset0:6 offset1:7
	ds_read2_b32 v[242:243], v96 offset0:16 offset1:17
	ds_read2_b32 v[244:245], v96 offset0:18 offset1:19
	ds_read2_b32 v[246:247], v96 offset0:20 offset1:21
	ds_read2_b32 v[248:249], v96 offset0:22 offset1:23
	ds_read2_b32 v[250:251], v96 offset0:32 offset1:33
	ds_read2_b32 v[252:253], v96 offset0:34 offset1:35
	ds_read2_b32 v[188:189], v96 offset0:36 offset1:37
	ds_read2_b32 v[190:191], v96 offset0:38 offset1:39
	ds_read2_b32 v[192:193], v96 offset0:48 offset1:49
	ds_read2_b32 v[194:195], v96 offset0:50 offset1:51
	ds_read2_b32 v[196:197], v96 offset0:52 offset1:53
	ds_read2_b32 v[198:199], v96 offset0:54 offset1:55
	s_waitcnt lgkmcnt(0)
	v_add_f32_e32 v64, v64, v234
	v_add_f32_e32 v65, v65, v235
	v_add_f32_e32 v66, v66, v236
	v_add_f32_e32 v67, v67, v237
	v_add_f32_e32 v68, v68, v238
	v_add_f32_e32 v69, v69, v239
	v_add_f32_e32 v70, v70, v240
	v_add_f32_e32 v71, v71, v241
	v_add_f32_e32 v72, v72, v242
	v_add_f32_e32 v73, v73, v243
	v_add_f32_e32 v74, v74, v244
	v_add_f32_e32 v75, v75, v245
	v_add_f32_e32 v76, v76, v246
	v_add_f32_e32 v77, v77, v247
	v_add_f32_e32 v78, v78, v248
	v_add_f32_e32 v79, v79, v249
	v_add_f32_e32 v80, v80, v250
	v_add_f32_e32 v81, v81, v251
	v_add_f32_e32 v82, v82, v252
	v_add_f32_e32 v83, v83, v253
	v_add_f32_e32 v84, v84, v188
	v_add_f32_e32 v85, v85, v189
	v_add_f32_e32 v86, v86, v190
	v_add_f32_e32 v87, v87, v191
	v_add_f32_e32 v88, v88, v192
	v_add_f32_e32 v89, v89, v193
	v_add_f32_e32 v90, v90, v194
	v_add_f32_e32 v91, v91, v195
	v_add_f32_e32 v92, v92, v196
	v_add_f32_e32 v93, v93, v197
	v_add_f32_e32 v94, v94, v198
	v_add_f32_e32 v95, v95, v199
	s_branch .LBB0_524
.Latt_slow_mt_b:
	ds_read2_b32 v[234:235], v96 offset1:1
	ds_read2_b32 v[236:237], v96 offset0:2 offset1:3
	ds_read2_b32 v[238:239], v96 offset0:4 offset1:5
	ds_read2_b32 v[240:241], v96 offset0:6 offset1:7
	s_waitcnt lgkmcnt(0)
	v_add_f32_e32 v64, v64, v234
	v_add_f32_e32 v65, v65, v235
	v_add_f32_e32 v66, v66, v236
	v_add_f32_e32 v67, v67, v237
	v_add_f32_e32 v68, v68, v238
	v_add_f32_e32 v69, v69, v239
	v_add_f32_e32 v70, v70, v240
	v_add_f32_e32 v71, v71, v241
	v_mov_b32_e32 v72, v215
	v_mov_b32_e32 v73, v215
	v_mov_b32_e32 v74, v215
	v_mov_b32_e32 v75, v215
	v_mov_b32_e32 v76, v215
	v_mov_b32_e32 v77, v215
	v_mov_b32_e32 v78, v215
	v_mov_b32_e32 v79, v215
	v_mov_b32_e32 v80, v215
	v_mov_b32_e32 v81, v215
	v_mov_b32_e32 v82, v215
	v_mov_b32_e32 v83, v215
	v_mov_b32_e32 v84, v215
	v_mov_b32_e32 v85, v215
	v_mov_b32_e32 v86, v215
	v_mov_b32_e32 v87, v215
	v_mov_b32_e32 v88, v215
	v_mov_b32_e32 v89, v215
	v_mov_b32_e32 v90, v215
	v_mov_b32_e32 v91, v215
	v_mov_b32_e32 v92, v215
	v_mov_b32_e32 v93, v215
	v_mov_b32_e32 v94, v215
	v_mov_b32_e32 v95, v215

; #define LAS __attribute__((address_space(3)))
; __global__ void __launch_bounds__(512, 2) mk_fwd(Args a) {
;     extern __shared__ __attribute__((aligned(16))) unsigned char lds_raw[];
;     LAS unsigned char* lds = (LAS unsigned char*)lds_raw;
;     cg::grid_group grid = cg::this_grid();
;     const int tid = threadIdx.x, lane = tid & 63, wave = __builtin_amdgcn_readfirstlane(tid >> 6);
	.amdhsa_kernel _Z6mk_fwd4Args
		.amdhsa_group_segment_fixed_size 0
		.amdhsa_private_segment_fixed_size 0
		.amdhsa_kernarg_size 464
		.amdhsa_user_sgpr_count 2
		.amdhsa_user_sgpr_dispatch_ptr 0
		.amdhsa_user_sgpr_queue_ptr 0
		.amdhsa_user_sgpr_kernarg_segment_ptr 1
		.amdhsa_user_sgpr_dispatch_id 0
		.amdhsa_user_sgpr_kernarg_preload_length 0
		.amdhsa_user_sgpr_kernarg_preload_offset 0
		.amdhsa_user_sgpr_private_segment_size 0
		.amdhsa_uses_dynamic_stack 0
		.amdhsa_enable_private_segment 0
		.amdhsa_system_sgpr_workgroup_id_x 1
		.amdhsa_system_sgpr_workgroup_id_y 0
		.amdhsa_system_sgpr_workgroup_id_z 0
		.amdhsa_system_sgpr_workgroup_info 0
		.amdhsa_system_vgpr_workitem_id 2
		.amdhsa_next_free_vgpr 256
		.amdhsa_next_free_sgpr 102
		.amdhsa_accum_offset 256
		.amdhsa_reserve_vcc 1
		.amdhsa_float_round_mode_32 0
		.amdhsa_float_round_mode_16_64 0
		.amdhsa_float_denorm_mode_32 3
		.amdhsa_float_denorm_mode_16_64 3
		.amdhsa_dx10_clamp 1
		.amdhsa_ieee_mode 1
		.amdhsa_fp16_overflow 0
		.amdhsa_tg_split 0
		.amdhsa_exception_fp_ieee_invalid_op 0
		.amdhsa_exception_fp_denorm_src 0
		.amdhsa_exception_fp_ieee_div_zero 0
		.amdhsa_exception_fp_ieee_overflow 0
		.amdhsa_exception_fp_ieee_underflow 0
		.amdhsa_exception_fp_ieee_inexact 0
		.amdhsa_exception_int_div_zero 0
	.end_amdhsa_kernel

; #define LAS __attribute__((address_space(3)))
; __global__ void __launch_bounds__(512, 2) mk_fwd(Args a) {
;     extern __shared__ __attribute__((aligned(16))) unsigned char lds_raw[];
;     LAS unsigned char* lds = (LAS unsigned char*)lds_raw;
;     cg::grid_group grid = cg::this_grid();
;     const int tid = threadIdx.x, lane = tid & 63, wave = __builtin_amdgcn_readfirstlane(tid >> 6);
amdhsa.kernels:
  - .agpr_count:     0
    .args:
      - .offset:         0
        .size:           208
        .value_kind:     by_value
      - .offset:         208
        .size:           4
        .value_kind:     hidden_block_count_x
      - .offset:         212
        .size:           4
        .value_kind:     hidden_block_count_y
      - .offset:         216
        .size:           4
        .value_kind:     hidden_block_count_z
      - .offset:         220
        .size:           2
        .value_kind:     hidden_group_size_x
      - .offset:         222
        .size:           2
        .value_kind:     hidden_group_size_y
      - .offset:         224
        .size:           2
        .value_kind:     hidden_group_size_z
      - .offset:         226
        .size:           2
        .value_kind:     hidden_remainder_x
      - .offset:         228
        .size:           2
        .value_kind:     hidden_remainder_y
      - .offset:         230
        .size:           2
        .value_kind:     hidden_remainder_z
      - .offset:         248
        .size:           8
        .value_kind:     hidden_global_offset_x
      - .offset:         256
        .size:           8
        .value_kind:     hidden_global_offset_y
      - .offset:         264
        .size:           8
        .value_kind:     hidden_global_offset_z
      - .offset:         272
        .size:           2
        .value_kind:     hidden_grid_dims
      - .offset:         296
        .size:           8
        .value_kind:     hidden_multigrid_sync_arg
      - .offset:         328
        .size:           4
        .value_kind:     hidden_dynamic_lds_size
    .group_segment_fixed_size: 0
    .kernarg_segment_align: 8
    .kernarg_segment_size: 464
    .language:       OpenCL C
    .language_version:
      - 2
      - 0
    .max_flat_workgroup_size: 512
    .name:           _Z6mk_fwd4Args
    .private_segment_fixed_size: 0
    .sgpr_count:     108
    .sgpr_spill_count: 110
    .symbol:         _Z6mk_fwd4Args.kd
    .uniform_work_group_size: 1
    .uses_dynamic_stack: false
    .vgpr_count:     256
    .vgpr_spill_count: 0
    .wavefront_size: 64
